# shiftw_rows on the f32 matrix cores (v_mfma_f32_16x16x4_f32, one wave per 16 weight rows) instead of per-row VALU dot products + 48 bpermutes
# baseline (speedup 1.0000x reference)
.Lph1_S:
	s_mov_b64 s[30:31], exec
	v_readfirstlane_b32 s3, v130
	v_and_b32_e32 v2, 15, v0
	v_bfe_u32 v3, v0, 4, 2
	v_and_b32_e32 v4, 7, v2
	v_lshlrev_b32_e32 v5, 11, v2
	v_lshl_or_b32 v5, v3, 4, v5
	v_mul_u32_u24_e32 v6, 0x6000, v4
	v_lshlrev_b32_e32 v7, 5, v3
	v_add_u32_e32 v6, v6, v7
	v_add_u32_e32 v6, 0x3000, v6
	v_mul_u32_u24_e32 v8, 0x5800, v4
	v_lshl_add_u32 v8, v3, 4, v8
	v_cmp_gt_u32_e64 s[16:17], 8, v2
.Lshw_blk:
	s_cmpk_ge_u32 s3, 0x2c0
	s_cbranch_scc1 .Lshw_done
	s_cmpk_ge_u32 s3, 0x160
	s_cselect_b32 s4, 1, 0
	s_mul_i32 s5, s4, 0x160
	s_sub_u32 s5, s3, s5
	s_mul_i32 s6, s4, 0xb00000
	s_lshl_b32 s7, s5, 15
	s_add_u32 s6, s6, s7
	s_add_u32 s6, s6, 0x700000
	s_add_u32 s8, s56, s6
	s_addc_u32 s9, s57, 0
	s_mul_i32 s6, s4, 0x36000
	s_add_u32 s6, s6, 0x2840000
	s_add_u32 s10, s56, s6
	s_addc_u32 s11, s57, 0
	s_mul_i32 s6, s4, 0x2c000
	s_lshl_b32 s7, s5, 6
	s_add_u32 s6, s6, s7
	s_add_u32 s6, s6, 0x1eeb4000
	s_add_u32 s12, s56, s6
	s_addc_u32 s13, s57, 0
	v_mov_b32_e32 v20, 0
	v_mov_b32_e32 v56, 0
	v_mov_b32_e32 v21, 0
	v_mov_b32_e32 v57, 0
	v_mov_b32_e32 v22, 0
	v_mov_b32_e32 v58, 0
	v_mov_b32_e32 v23, 0
	v_mov_b32_e32 v59, 0
	global_load_dwordx4 v[24:27], v5, s[8:9]
	global_load_dwordx4 v[28:31], v6, s[10:11]
	global_load_dwordx4 v[32:35], v6, s[10:11] offset:16
	s_mov_b32 s14, 16
.Lshw_j:
	global_load_dwordx4 v[36:39], v5, s[8:9] offset:64
	global_load_dwordx4 v[40:43], v6, s[10:11] offset:128
	global_load_dwordx4 v[44:47], v6, s[10:11] offset:144
	s_waitcnt vmcnt(3)
	v_lshlrev_b32_e32 v48, 16, v24
	v_and_b32_e32 v49, 0xffff0000, v24
	v_lshlrev_b32_e32 v50, 16, v25
	v_and_b32_e32 v51, 0xffff0000, v25
	v_lshlrev_b32_e32 v52, 16, v26
	v_and_b32_e32 v53, 0xffff0000, v26
	v_lshlrev_b32_e32 v54, 16, v27
	v_and_b32_e32 v55, 0xffff0000, v27
	v_mfma_f32_16x16x4_f32 v[20:23], v48, v28, v[20:23]
	v_mfma_f32_16x16x4_f32 v[56:59], v49, v29, v[56:59]
	v_mfma_f32_16x16x4_f32 v[20:23], v50, v30, v[20:23]
	v_mfma_f32_16x16x4_f32 v[56:59], v51, v31, v[56:59]
	v_mfma_f32_16x16x4_f32 v[20:23], v52, v32, v[20:23]
	v_mfma_f32_16x16x4_f32 v[56:59], v53, v33, v[56:59]
	v_mfma_f32_16x16x4_f32 v[20:23], v54, v34, v[20:23]
	v_mfma_f32_16x16x4_f32 v[56:59], v55, v35, v[56:59]
	s_add_u32 s8, s8, 0x80
	s_addc_u32 s9, s9, 0
	s_add_u32 s10, s10, 0x100
	s_addc_u32 s11, s11, 0
	global_load_dwordx4 v[24:27], v5, s[8:9]
	global_load_dwordx4 v[28:31], v6, s[10:11]
	global_load_dwordx4 v[32:35], v6, s[10:11] offset:16
	s_waitcnt vmcnt(3)
	v_lshlrev_b32_e32 v48, 16, v36
	v_and_b32_e32 v49, 0xffff0000, v36
	v_lshlrev_b32_e32 v50, 16, v37
	v_and_b32_e32 v51, 0xffff0000, v37
	v_lshlrev_b32_e32 v52, 16, v38
	v_and_b32_e32 v53, 0xffff0000, v38
	v_lshlrev_b32_e32 v54, 16, v39
	v_and_b32_e32 v55, 0xffff0000, v39
	v_mfma_f32_16x16x4_f32 v[20:23], v48, v40, v[20:23]
	v_mfma_f32_16x16x4_f32 v[56:59], v49, v41, v[56:59]
	v_mfma_f32_16x16x4_f32 v[20:23], v50, v42, v[20:23]
	v_mfma_f32_16x16x4_f32 v[56:59], v51, v43, v[56:59]
	v_mfma_f32_16x16x4_f32 v[20:23], v52, v44, v[20:23]
	v_mfma_f32_16x16x4_f32 v[56:59], v53, v45, v[56:59]
	v_mfma_f32_16x16x4_f32 v[20:23], v54, v46, v[20:23]
	v_mfma_f32_16x16x4_f32 v[56:59], v55, v47, v[56:59]
	s_sub_u32 s14, s14, 1
	s_cmp_lg_u32 s14, 0
	s_cbranch_scc1 .Lshw_j
	s_waitcnt vmcnt(0)
	s_nop 7
	s_nop 7
	v_add_f32_e32 v20, v20, v56
	v_add_f32_e32 v21, v21, v57
	v_add_f32_e32 v22, v22, v58
	v_add_f32_e32 v23, v23, v59
	s_mov_b64 exec, s[16:17]
	global_store_dwordx4 v8, v[20:23], s[12:13]
	s_mov_b64 exec, s[30:31]
	s_add_u32 s3, s3, s28
	s_branch .Lshw_blk
.Lshw_done:
.LBB0_168:
	s_or_b64 exec, exec, s[30:31]
	s_cmp_eq_u32 s98, 1
	s_cbranch_scc1 .Lph1_again
